# merge GEMM stagger moved inside each XCD: every second workgroup of an XCD (bit 3 of the block id) starts ~10us later, instead of XCDs 4-7; otherwise v20
# speedup vs baseline: 1.0204x; 1.0011x over previous
.LBB0_567:
	s_cmp_lt_i32 s76, 8
	s_cselect_b64 s[12:13], -1, 0
	s_cmp_gt_i32 s77, 7
	s_cselect_b64 s[4:5], -1, 0
	s_and_b64 s[4:5], s[12:13], s[4:5]
	s_andn2_b64 vcc, exec, s[4:5]
	v_bfe_u32 v223, v196, 2, 2
	s_cbranch_vccnz .LBB0_692
	s_cmpk_lt_i32 s2, 0x400
	s_cselect_b64 s[8:9], -1, 0
	s_cmpk_gt_i32 s2, 0x3ff
	s_mov_b64 s[6:7], s[0:1]
	v_readfirstlane_b32 s20, v196
	s_waitcnt vmcnt(0) lgkmcnt(0)
	s_barrier
	s_cbranch_scc1 .LBB0_570
	s_bfe_u32 s99, s2, 0x10003
	s_cmp_eq_u32 s99, 0
	s_cbranch_scc1 .Lstg7_done
